# PH1 mini tasks: 16 of the second k-trip's operand loads issued with the first trip's loads
# baseline (speedup 1.0000x reference)
; #define SBAR() __builtin_amdgcn_sched_barrier(0)
; template <int KIND>
; __device__ __forceinline__ void mini_task(const Ptrs& P, const bf16* A, int lda, const bf16* B, int ldb, int K, int row0, int cb, LAS unsigned char* lds) {
;     ...
;     const bf16* ap = A + (size_t)r32 * lda + wave * kw + hi * 8; const bf16* bp = B + (size_t)r32 * ldb + wave * kw + hi * 8;
;     const int erow = row0 + (tid >> 4); const bool emeta = row0 >= MTOK;
;     float e_rs = 0.f; f32x4 e_cs0 = {}, e_cs1 = {};
;     if constexpr (KIND == MK_KVUP) e_rs = P.ssq_kv_()[erow]; else e_rs = P.rs1_()[erow];
;     if constexpr (KIND == MK_KR) { const int epos = emeta ? ((tid >> 4) < NMETA ? (tid >> 4) : 0) : NMETA + (erow & 4095); const int ejp = (tid & 15) >> 1;
;         e_cs0 = *(const f32x4*)(P.cs_() + (size_t)epos * 32 + ejp * 4); e_cs1 = *(const f32x4*)(P.cs_() + (size_t)epos * 32 + ejp * 4 + 2); }
;     f32x16 c0 = {}, c1 = {};
;     SBAR();
;     if (kw >= 128) {
;         for (int k = 0; k < kw; k += 128) {
;             bf16x8 a[8], b0[8], b1[8];
; #pragma unroll
;             for (int j = 0; j < 8; ++j) { a[j] = *(const bf16x8*)(ap + k + 16 * j); b0[j] = *(const bf16x8*)(bp + k + 16 * j); b1[j] = *(const bf16x8*)(bp + (size_t)32 * ldb + k + 16 * j); }
;             SBAR();
; #pragma unroll
;             for (int j = 0; j < 8; ++j) { c0 = __builtin_amdgcn_mfma_f32_32x32x16_bf16(a[j], b0[j], c0, 0, 0, 0); c1 = __builtin_amdgcn_mfma_f32_32x32x16_bf16(a[j], b1[j], c1, 0, 0, 0); }
;             SBAR(); }
; __global__ void __launch_bounds__(NWAVES * 64, 2) hybrid_fwd(Args args) {
;     ...
;         for (int tk = vcu; tk < 257 + 24; tk += G) {
;             if (tk < 257) mini_task<MK_KR>(P, P.xb_() + (size_t)tk * 32 * DM, DM, P.win_() + (size_t)6144 * DM, DM, DM, tk * 32, 0, lds);
;             else { const int cbm = tk - 257;
;                 if (cbm < 8) mini_task<MK_KVLAT>(P, P.xb_() + (size_t)MTOK * DM, DM, P.win_() + (size_t)(512 + 64 * cbm) * DM, DM, DM, MTOK, cbm, lds);
;                 else mini_task<MK_UMETA>(P, P.xb_() + (size_t)MTOK * DM, DM, P.win_() + (size_t)(1024 + 64 * (cbm - 8)) * DM, DM, DM, MTOK, cbm - 8, lds); } }
.LBB0_337:
	s_cmpk_gt_i32 s29, 0x100
	s_mov_b64 s[8:9], -1
	s_cbranch_scc0 .LBB0_346
	s_add_i32 s12, s16, 0xffffc1c0
	s_lshl_b64 s[8:9], s[12:13], 12
	s_cmpk_gt_u32 s29, 0x108
	v_lshl_add_u64 v[34:35], v[46:47], 0, s[8:9]
	s_mov_b64 s[8:9], -1
	s_cbranch_scc0 .LBB0_342
	global_load_dword v36, v[48:49], off
	v_readfirstlane_b32 s8, v0
	s_lshr_b32 s8, s8, 6
	s_lshl_b32 s12, s8, 9
	v_lshl_add_u64 v[2:3], v[34:35], 0, s[12:13]
	v_mov_b32_e32 v73, v43
	v_lshl_add_u64 v[158:159], v[44:45], 0, s[12:13]
	v_lshl_add_u64 v[160:161], v[2:3], 0, v[72:73]
	v_add_co_u32_e32 v166, vcc, 0x20000, v160
	s_nop 1
	v_addc_co_u32_e32 v167, vcc, 0, v161, vcc
	global_load_dwordx4 v[18:21], v[158:159], off
	global_load_dwordx4 v[38:41], v[158:159], off offset:32
	global_load_dwordx4 v[2:5], v[160:161], off
	global_load_dwordx4 v[78:81], v[160:161], off offset:32
	global_load_dwordx4 v[22:25], v[166:167], off
	global_load_dwordx4 v[82:85], v[166:167], off offset:32
	global_load_dwordx4 v[86:89], v[158:159], off offset:64
	global_load_dwordx4 v[90:93], v[158:159], off offset:96
	global_load_dwordx4 v[94:97], v[160:161], off offset:64
	global_load_dwordx4 v[98:101], v[160:161], off offset:96
	global_load_dwordx4 v[102:105], v[166:167], off offset:64
	global_load_dwordx4 v[106:109], v[166:167], off offset:96
	global_load_dwordx4 v[110:113], v[158:159], off offset:128
	global_load_dwordx4 v[114:117], v[158:159], off offset:160
	global_load_dwordx4 v[118:121], v[160:161], off offset:128
	global_load_dwordx4 v[122:125], v[160:161], off offset:160
	global_load_dwordx4 v[126:129], v[166:167], off offset:128
	global_load_dwordx4 v[130:133], v[166:167], off offset:160
	global_load_dwordx4 v[134:137], v[158:159], off offset:192
	global_load_dwordx4 v[138:141], v[158:159], off offset:224
	global_load_dwordx4 v[142:145], v[160:161], off offset:192
	global_load_dwordx4 v[146:149], v[160:161], off offset:224
	global_load_dwordx4 v[150:153], v[166:167], off offset:192
	global_load_dwordx4 v[154:157], v[166:167], off offset:224
	global_load_dwordx4 v[180:183], v[158:159], off offset:256
	global_load_dwordx4 v[184:187], v[158:159], off offset:288
	global_load_dwordx4 v[188:191], v[160:161], off offset:256
	global_load_dwordx4 v[192:195], v[160:161], off offset:288
	global_load_dwordx4 v[196:199], v[166:167], off offset:256
	global_load_dwordx4 v[200:203], v[166:167], off offset:288
	global_load_dwordx4 v[204:207], v[158:159], off offset:320
	global_load_dwordx4 v[208:211], v[158:159], off offset:352
	global_load_dwordx4 v[212:215], v[160:161], off offset:320
	global_load_dwordx4 v[216:219], v[160:161], off offset:352
	global_load_dwordx4 v[220:223], v[166:167], off offset:320
	global_load_dwordx4 v[224:227], v[166:167], off offset:352
	global_load_dwordx4 v[228:231], v[158:159], off offset:384
	global_load_dwordx4 v[232:235], v[158:159], off offset:416
	global_load_dwordx4 v[236:239], v[160:161], off offset:384
	global_load_dwordx4 v[240:243], v[160:161], off offset:416
	s_waitcnt vmcnt(37)
	v_mfma_f32_32x32x16_bf16 v[2:17], v[18:21], v[2:5], 0
	s_waitcnt vmcnt(35)
	v_mfma_f32_32x32x16_bf16 v[18:33], v[18:21], v[22:25], 0
	v_mfma_f32_32x32x16_bf16 v[2:17], v[38:41], v[78:81], v[2:17]
	s_waitcnt vmcnt(34)
	v_mfma_f32_32x32x16_bf16 v[18:33], v[38:41], v[82:85], v[18:33]
	s_waitcnt vmcnt(31)
	v_mfma_f32_32x32x16_bf16 v[2:17], v[86:89], v[94:97], v[2:17]
	s_waitcnt vmcnt(29)
	v_mfma_f32_32x32x16_bf16 v[18:33], v[86:89], v[102:105], v[18:33]
	v_mfma_f32_32x32x16_bf16 v[2:17], v[90:93], v[98:101], v[2:17]
	s_waitcnt vmcnt(28)
	v_mfma_f32_32x32x16_bf16 v[18:33], v[90:93], v[106:109], v[18:33]
	s_waitcnt vmcnt(25)
	v_mfma_f32_32x32x16_bf16 v[2:17], v[110:113], v[118:121], v[2:17]
	s_waitcnt vmcnt(23)
	v_mfma_f32_32x32x16_bf16 v[18:33], v[110:113], v[126:129], v[18:33]
	v_mfma_f32_32x32x16_bf16 v[2:17], v[114:117], v[122:125], v[2:17]
	s_waitcnt vmcnt(22)
	v_mfma_f32_32x32x16_bf16 v[18:33], v[114:117], v[130:133], v[18:33]
	s_waitcnt vmcnt(19)
	v_mfma_f32_32x32x16_bf16 v[2:17], v[134:137], v[142:145], v[2:17]
	s_waitcnt vmcnt(17)
	v_mfma_f32_32x32x16_bf16 v[18:33], v[134:137], v[150:153], v[18:33]
	v_mfma_f32_32x32x16_bf16 v[2:17], v[138:141], v[146:149], v[2:17]
	s_waitcnt vmcnt(16)
; #define LAS __attribute__((address_space(3)))
; #define SBAR() __builtin_amdgcn_sched_barrier(0)
; template <int KIND>
; __device__ __forceinline__ void mini_task(const Ptrs& P, const bf16* A, int lda, const bf16* B, int ldb, int K, int row0, int cb, LAS unsigned char* lds) {
;     ...
;         for (int k = 0; k < kw; k += 128) {
;             bf16x8 a[8], b0[8], b1[8];
; #pragma unroll
;             for (int j = 0; j < 8; ++j) { a[j] = *(const bf16x8*)(ap + k + 16 * j); b0[j] = *(const bf16x8*)(bp + k + 16 * j); b1[j] = *(const bf16x8*)(bp + (size_t)32 * ldb + k + 16 * j); }
;             SBAR();
; #pragma unroll
;             for (int j = 0; j < 8; ++j) { c0 = __builtin_amdgcn_mfma_f32_32x32x16_bf16(a[j], b0[j], c0, 0, 0, 0); c1 = __builtin_amdgcn_mfma_f32_32x32x16_bf16(a[j], b1[j], c1, 0, 0, 0); }
;             SBAR(); }
;     } else {
;         for (int k = 0; k < kw; k += 64) {
;             bf16x8 a[4], b0[4], b1[4];
; #pragma unroll
;             for (int j = 0; j < 4; ++j) { a[j] = *(const bf16x8*)(ap + k + 16 * j); b0[j] = *(const bf16x8*)(bp + k + 16 * j); b1[j] = *(const bf16x8*)(bp + (size_t)32 * ldb + k + 16 * j); }
;             SBAR();
; #pragma unroll
;             for (int j = 0; j < 4; ++j) { c0 = __builtin_amdgcn_mfma_f32_32x32x16_bf16(a[j], b0[j], c0, 0, 0, 0); c1 = __builtin_amdgcn_mfma_f32_32x32x16_bf16(a[j], b1[j], c1, 0, 0, 0); } } }
;     LAS float* red = (LAS float*)lds + wave * 2048;
; #pragma unroll
;     for (int r = 0; r < 16; ++r) { const int rw = (r & 3) + 8 * (r >> 2) + 4 * hi; red[rw * 64 + r32] = c0[r]; red[rw * 64 + 32 + r32] = c1[r]; }
;     __syncthreads();
;     const int row = tid >> 4, cg = tid & 15;
;     f32x4 v = {0.f, 0.f, 0.f, 0.f};
; #pragma unroll
;     for (int w = 0; w < 8; ++w) v += *(const LAS f32x4*)((const LAS float*)lds + w * 2048 + row * 64 + cg * 4);
;     ...
;     } else if constexpr (KIND == MK_UMETA) {
;         v *= e_rs;
;         if (row < NMETA) *(f32x4*)(P.umeta_() + row * 1024 + cb * 64 + cg * 4) = v;
	v_mfma_f32_32x32x16_bf16 v[18:33], v[138:141], v[154:157], v[18:33]
	global_load_dwordx4 v[138:141], v[166:167], off offset:384
	global_load_dwordx4 v[142:145], v[166:167], off offset:416
	global_load_dwordx4 v[146:149], v[158:159], off offset:448
	global_load_dwordx4 v[150:153], v[158:159], off offset:480
	global_load_dwordx4 v[154:157], v[160:161], off offset:448
	s_nop 0
	global_load_dwordx4 v[158:161], v[160:161], off offset:480
	s_nop 0
	global_load_dwordx4 v[162:165], v[166:167], off offset:448
	s_nop 0
	global_load_dwordx4 v[166:169], v[166:167], off offset:480
	s_waitcnt vmcnt(21)
	v_mfma_f32_32x32x16_bf16 v[2:17], v[180:183], v[188:191], v[2:17]
	s_waitcnt vmcnt(19)
	v_mfma_f32_32x32x16_bf16 v[18:33], v[180:183], v[196:199], v[18:33]
	v_mfma_f32_32x32x16_bf16 v[2:17], v[184:187], v[192:195], v[2:17]
	s_waitcnt vmcnt(18)
	v_mfma_f32_32x32x16_bf16 v[18:33], v[184:187], v[200:203], v[18:33]
	s_waitcnt vmcnt(15)
	v_mfma_f32_32x32x16_bf16 v[2:17], v[204:207], v[212:215], v[2:17]
	s_waitcnt vmcnt(13)
	v_mfma_f32_32x32x16_bf16 v[18:33], v[204:207], v[220:223], v[18:33]
	v_mfma_f32_32x32x16_bf16 v[2:17], v[208:211], v[216:219], v[2:17]
	s_waitcnt vmcnt(12)
	v_mfma_f32_32x32x16_bf16 v[18:33], v[208:211], v[224:227], v[18:33]
	s_waitcnt vmcnt(9)
	v_mfma_f32_32x32x16_bf16 v[2:17], v[228:231], v[236:239], v[2:17]
	s_waitcnt vmcnt(7)
	v_mfma_f32_32x32x16_bf16 v[18:33], v[228:231], v[138:141], v[18:33]
	v_mfma_f32_32x32x16_bf16 v[2:17], v[232:235], v[240:243], v[2:17]
	s_waitcnt vmcnt(6)
	v_mfma_f32_32x32x16_bf16 v[18:33], v[232:235], v[142:145], v[18:33]
	s_waitcnt vmcnt(3)
	v_mfma_f32_32x32x16_bf16 v[2:17], v[146:149], v[154:157], v[2:17]
	s_waitcnt vmcnt(1)
	v_mfma_f32_32x32x16_bf16 v[18:33], v[146:149], v[162:165], v[18:33]
	v_mfma_f32_32x32x16_bf16 v[2:17], v[150:153], v[158:161], v[2:17]
	s_waitcnt vmcnt(0)
	v_mfma_f32_32x32x16_bf16 v[18:33], v[150:153], v[166:169], v[18:33]
	v_lshl_add_u32 v37, s8, 13, v74
	s_nop 10
	ds_write2_b32 v37, v2, v18 offset1:32
	ds_write2_b32 v37, v3, v19 offset0:64 offset1:96
	ds_write2_b32 v37, v4, v20 offset0:128 offset1:160
	ds_write2_b32 v37, v5, v21 offset0:192 offset1:224
	v_add_u32_e32 v2, 0x800, v37
	ds_write2_b32 v2, v6, v22 offset1:32
	ds_write2_b32 v2, v7, v23 offset0:64 offset1:96
	ds_write2_b32 v2, v8, v24 offset0:128 offset1:160
	ds_write2_b32 v2, v9, v25 offset0:192 offset1:224
	v_add_u32_e32 v2, 0x1000, v37
	ds_write2_b32 v2, v10, v26 offset1:32
	ds_write2_b32 v2, v11, v27 offset0:64 offset1:96
	ds_write2_b32 v2, v12, v28 offset0:128 offset1:160
	ds_write2_b32 v2, v13, v29 offset0:192 offset1:224
	v_add_u32_e32 v2, 0x1800, v37
	ds_write2_b32 v2, v14, v30 offset1:32
	ds_write2_b32 v2, v15, v31 offset0:64 offset1:96
	ds_write2_b32 v2, v16, v32 offset0:128 offset1:160
	ds_write2_b32 v2, v17, v33 offset0:192 offset1:224
	s_waitcnt lgkmcnt(0)
	s_barrier
	s_and_saveexec_b64 s[8:9], s[6:7]
	s_cbranch_execz .LBB0_341
	v_add_u32_e32 v18, v75, v50
	ds_read_b128 v[2:5], v18
	ds_read_b128 v[6:9], v18 offset:8192
	ds_read_b128 v[10:13], v18 offset:16384
	ds_read_b128 v[14:17], v18 offset:24576
	s_mov_b32 s17, s13
	s_waitcnt lgkmcnt(3)
	v_pk_add_f32 v[4:5], v[4:5], 0 op_sel_hi:[1,0]
	v_pk_add_f32 v[2:3], v[2:3], 0 op_sel_hi:[1,0]
	s_waitcnt lgkmcnt(2)
	v_pk_add_f32 v[4:5], v[4:5], v[8:9]
	v_pk_add_f32 v[6:7], v[2:3], v[6:7]
	s_waitcnt lgkmcnt(1)
	v_pk_add_f32 v[8:9], v[4:5], v[12:13]
	ds_read_b128 v[2:5], v18 offset:32768
	v_pk_add_f32 v[6:7], v[6:7], v[10:11]
	s_waitcnt lgkmcnt(1)
	v_pk_add_f32 v[10:11], v[8:9], v[16:17]
	v_pk_add_f32 v[14:15], v[6:7], v[14:15]
	ds_read_b128 v[6:9], v18 offset:40960
	s_waitcnt lgkmcnt(1)
	v_pk_add_f32 v[16:17], v[10:11], v[4:5]
	ds_read_b128 v[10:13], v18 offset:49152
	v_pk_add_f32 v[14:15], v[14:15], v[2:3]
	ds_read_b128 v[2:5], v18 offset:57344
	s_waitcnt lgkmcnt(2)
	v_pk_add_f32 v[6:7], v[14:15], v[6:7]
	v_pk_add_f32 v[8:9], v[16:17], v[8:9]
	s_waitcnt lgkmcnt(1)
	v_pk_add_f32 v[6:7], v[6:7], v[10:11]
	v_pk_add_f32 v[8:9], v[8:9], v[12:13]
	s_waitcnt lgkmcnt(0)
	v_pk_add_f32 v[2:3], v[6:7], v[2:3]
	v_lshl_add_u64 v[6:7], s[16:17], 2, v[52:53]
	v_pk_add_f32 v[4:5], v[8:9], v[4:5]
	v_add_co_u32_e32 v6, vcc, 0x37f000, v6
	v_pk_mul_f32 v[4:5], v[36:37], v[4:5] op_sel_hi:[0,1]
	v_pk_mul_f32 v[2:3], v[36:37], v[2:3] op_sel_hi:[0,1]
	v_addc_co_u32_e32 v7, vcc, 0, v7, vcc
	global_store_dwordx4 v[6:7], v[2:5], off offset:1792

; #define LAS __attribute__((address_space(3)))
; #define SBAR() __builtin_amdgcn_sched_barrier(0)
; template <int KIND>
; __device__ __forceinline__ void mini_task(const Ptrs& P, const bf16* A, int lda, const bf16* B, int ldb, int K, int row0, int cb, LAS unsigned char* lds) {
;     ...
;     const bf16* ap = A + (size_t)r32 * lda + wave * kw + hi * 8; const bf16* bp = B + (size_t)r32 * ldb + wave * kw + hi * 8;
;     const int erow = row0 + (tid >> 4); const bool emeta = row0 >= MTOK;
;     float e_rs = 0.f; f32x4 e_cs0 = {}, e_cs1 = {};
;     if constexpr (KIND == MK_KVUP) e_rs = P.ssq_kv_()[erow]; else e_rs = P.rs1_()[erow];
;     if constexpr (KIND == MK_KR) { const int epos = emeta ? ((tid >> 4) < NMETA ? (tid >> 4) : 0) : NMETA + (erow & 4095); const int ejp = (tid & 15) >> 1;
;         e_cs0 = *(const f32x4*)(P.cs_() + (size_t)epos * 32 + ejp * 4); e_cs1 = *(const f32x4*)(P.cs_() + (size_t)epos * 32 + ejp * 4 + 2); }
;     f32x16 c0 = {}, c1 = {};
;     SBAR();
;     if (kw >= 128) {
;         for (int k = 0; k < kw; k += 128) {
;             bf16x8 a[8], b0[8], b1[8];
; #pragma unroll
;             for (int j = 0; j < 8; ++j) { a[j] = *(const bf16x8*)(ap + k + 16 * j); b0[j] = *(const bf16x8*)(bp + k + 16 * j); b1[j] = *(const bf16x8*)(bp + (size_t)32 * ldb + k + 16 * j); }
;             SBAR();
; #pragma unroll
;             for (int j = 0; j < 8; ++j) { c0 = __builtin_amdgcn_mfma_f32_32x32x16_bf16(a[j], b0[j], c0, 0, 0, 0); c1 = __builtin_amdgcn_mfma_f32_32x32x16_bf16(a[j], b1[j], c1, 0, 0, 0); }
;             SBAR(); }
;     } else {
;         for (int k = 0; k < kw; k += 64) {
;             bf16x8 a[4], b0[4], b1[4];
; #pragma unroll
;             for (int j = 0; j < 4; ++j) { a[j] = *(const bf16x8*)(ap + k + 16 * j); b0[j] = *(const bf16x8*)(bp + k + 16 * j); b1[j] = *(const bf16x8*)(bp + (size_t)32 * ldb + k + 16 * j); }
;             SBAR();
; #pragma unroll
;             for (int j = 0; j < 4; ++j) { c0 = __builtin_amdgcn_mfma_f32_32x32x16_bf16(a[j], b0[j], c0, 0, 0, 0); c1 = __builtin_amdgcn_mfma_f32_32x32x16_bf16(a[j], b1[j], c1, 0, 0, 0); } } }
;     LAS float* red = (LAS float*)lds + wave * 2048;
; #pragma unroll
;     for (int r = 0; r < 16; ++r) { const int rw = (r & 3) + 8 * (r >> 2) + 4 * hi; red[rw * 64 + r32] = c0[r]; red[rw * 64 + 32 + r32] = c1[r]; }
;     __syncthreads();
.LBB0_342:
	s_and_b64 vcc, exec, s[8:9]
	s_cbranch_vccz .LBB0_350
	global_load_dword v42, v[54:55], off
	v_readfirstlane_b32 s8, v0
	s_lshr_b32 s8, s8, 6
	s_lshl_b32 s12, s8, 9
	v_lshl_add_u64 v[2:3], v[34:35], 0, s[12:13]
	v_mov_b32_e32 v73, v43
	v_lshl_add_u64 v[154:155], v[44:45], 0, s[12:13]
	v_lshl_add_u64 v[156:157], v[2:3], 0, v[72:73]
	v_add_co_u32_e32 v162, vcc, 0x20000, v156
	s_nop 1
	v_addc_co_u32_e32 v163, vcc, 0, v157, vcc
	global_load_dwordx4 v[18:21], v[154:155], off
	global_load_dwordx4 v[34:37], v[154:155], off offset:32
	global_load_dwordx4 v[2:5], v[156:157], off
	global_load_dwordx4 v[38:41], v[156:157], off offset:32
	global_load_dwordx4 v[22:25], v[162:163], off
	global_load_dwordx4 v[78:81], v[162:163], off offset:32
	global_load_dwordx4 v[82:85], v[154:155], off offset:64
	global_load_dwordx4 v[86:89], v[154:155], off offset:96
	global_load_dwordx4 v[90:93], v[156:157], off offset:64
	global_load_dwordx4 v[94:97], v[156:157], off offset:96
	global_load_dwordx4 v[98:101], v[162:163], off offset:64
	global_load_dwordx4 v[102:105], v[162:163], off offset:96
	global_load_dwordx4 v[106:109], v[154:155], off offset:128
	global_load_dwordx4 v[110:113], v[154:155], off offset:160
	global_load_dwordx4 v[114:117], v[156:157], off offset:128
	global_load_dwordx4 v[118:121], v[156:157], off offset:160
	global_load_dwordx4 v[122:125], v[162:163], off offset:128
	global_load_dwordx4 v[126:129], v[162:163], off offset:160
	global_load_dwordx4 v[130:133], v[154:155], off offset:192
	global_load_dwordx4 v[134:137], v[154:155], off offset:224
	global_load_dwordx4 v[138:141], v[156:157], off offset:192
	global_load_dwordx4 v[142:145], v[156:157], off offset:224
	global_load_dwordx4 v[146:149], v[162:163], off offset:192
	global_load_dwordx4 v[150:153], v[162:163], off offset:224
	global_load_dwordx4 v[180:183], v[154:155], off offset:256
	global_load_dwordx4 v[184:187], v[154:155], off offset:288
	global_load_dwordx4 v[188:191], v[156:157], off offset:256
	global_load_dwordx4 v[192:195], v[156:157], off offset:288
	global_load_dwordx4 v[196:199], v[162:163], off offset:256
	global_load_dwordx4 v[200:203], v[162:163], off offset:288
	global_load_dwordx4 v[204:207], v[154:155], off offset:320
	global_load_dwordx4 v[208:211], v[154:155], off offset:352
	global_load_dwordx4 v[212:215], v[156:157], off offset:320
	global_load_dwordx4 v[216:219], v[156:157], off offset:352
	global_load_dwordx4 v[220:223], v[162:163], off offset:320
	global_load_dwordx4 v[224:227], v[162:163], off offset:352
	global_load_dwordx4 v[228:231], v[154:155], off offset:384
	global_load_dwordx4 v[232:235], v[154:155], off offset:416
	global_load_dwordx4 v[236:239], v[156:157], off offset:384
	global_load_dwordx4 v[240:243], v[156:157], off offset:416
	s_waitcnt vmcnt(37)
	v_mfma_f32_32x32x16_bf16 v[2:17], v[18:21], v[2:5], 0
	s_waitcnt vmcnt(35)
	v_mfma_f32_32x32x16_bf16 v[18:33], v[18:21], v[22:25], 0
	v_mfma_f32_32x32x16_bf16 v[2:17], v[34:37], v[38:41], v[2:17]
	s_waitcnt vmcnt(34)
	v_mfma_f32_32x32x16_bf16 v[18:33], v[34:37], v[78:81], v[18:33]
	s_waitcnt vmcnt(31)
	v_mfma_f32_32x32x16_bf16 v[2:17], v[82:85], v[90:93], v[2:17]
	s_waitcnt vmcnt(29)
	v_mfma_f32_32x32x16_bf16 v[18:33], v[82:85], v[98:101], v[18:33]
	v_mfma_f32_32x32x16_bf16 v[2:17], v[86:89], v[94:97], v[2:17]
	s_waitcnt vmcnt(28)
	v_mfma_f32_32x32x16_bf16 v[18:33], v[86:89], v[102:105], v[18:33]
	s_waitcnt vmcnt(25)
	v_mfma_f32_32x32x16_bf16 v[2:17], v[106:109], v[114:117], v[2:17]
	s_waitcnt vmcnt(23)
	v_mfma_f32_32x32x16_bf16 v[18:33], v[106:109], v[122:125], v[18:33]
	v_mfma_f32_32x32x16_bf16 v[2:17], v[110:113], v[118:121], v[2:17]
	s_waitcnt vmcnt(22)
	v_mfma_f32_32x32x16_bf16 v[18:33], v[110:113], v[126:129], v[18:33]
	s_waitcnt vmcnt(19)
	v_mfma_f32_32x32x16_bf16 v[2:17], v[130:133], v[138:141], v[2:17]
	s_waitcnt vmcnt(17)
	v_mfma_f32_32x32x16_bf16 v[18:33], v[130:133], v[146:149], v[18:33]
	v_mfma_f32_32x32x16_bf16 v[2:17], v[134:137], v[142:145], v[2:17]
	s_waitcnt vmcnt(16)
	v_mfma_f32_32x32x16_bf16 v[18:33], v[134:137], v[150:153], v[18:33]
	global_load_dwordx4 v[134:137], v[162:163], off offset:384
	global_load_dwordx4 v[138:141], v[162:163], off offset:416
	global_load_dwordx4 v[142:145], v[154:155], off offset:448
	global_load_dwordx4 v[146:149], v[154:155], off offset:480
	global_load_dwordx4 v[150:153], v[156:157], off offset:448
	s_nop 0
	global_load_dwordx4 v[154:157], v[156:157], off offset:480
	s_nop 0
	global_load_dwordx4 v[158:161], v[162:163], off offset:448
	s_nop 0
	global_load_dwordx4 v[162:165], v[162:163], off offset:480
	s_waitcnt vmcnt(21)
	v_mfma_f32_32x32x16_bf16 v[2:17], v[180:183], v[188:191], v[2:17]
	s_waitcnt vmcnt(19)
	v_mfma_f32_32x32x16_bf16 v[18:33], v[180:183], v[196:199], v[18:33]
	v_mfma_f32_32x32x16_bf16 v[2:17], v[184:187], v[192:195], v[2:17]
	s_waitcnt vmcnt(18)
	v_mfma_f32_32x32x16_bf16 v[18:33], v[184:187], v[200:203], v[18:33]
	s_waitcnt vmcnt(15)
	v_mfma_f32_32x32x16_bf16 v[2:17], v[204:207], v[212:215], v[2:17]
	s_waitcnt vmcnt(13)
	v_mfma_f32_32x32x16_bf16 v[18:33], v[204:207], v[220:223], v[18:33]
	v_mfma_f32_32x32x16_bf16 v[2:17], v[208:211], v[216:219], v[2:17]
	s_waitcnt vmcnt(12)
	v_mfma_f32_32x32x16_bf16 v[18:33], v[208:211], v[224:227], v[18:33]
	s_waitcnt vmcnt(9)
	v_mfma_f32_32x32x16_bf16 v[2:17], v[228:231], v[236:239], v[2:17]
	s_waitcnt vmcnt(7)
	v_mfma_f32_32x32x16_bf16 v[18:33], v[228:231], v[134:137], v[18:33]
	v_mfma_f32_32x32x16_bf16 v[2:17], v[232:235], v[240:243], v[2:17]
	s_waitcnt vmcnt(6)
	v_mfma_f32_32x32x16_bf16 v[18:33], v[232:235], v[138:141], v[18:33]
	s_waitcnt vmcnt(3)
	v_mfma_f32_32x32x16_bf16 v[2:17], v[142:145], v[150:153], v[2:17]
	s_waitcnt vmcnt(1)
	v_mfma_f32_32x32x16_bf16 v[18:33], v[142:145], v[158:161], v[18:33]
	v_mfma_f32_32x32x16_bf16 v[2:17], v[146:149], v[154:157], v[2:17]
	s_waitcnt vmcnt(0)
	v_mfma_f32_32x32x16_bf16 v[18:33], v[146:149], v[162:165], v[18:33]
	v_lshl_add_u32 v34, s8, 13, v74
	s_nop 10
	ds_write2_b32 v34, v2, v18 offset1:32
	ds_write2_b32 v34, v3, v19 offset0:64 offset1:96
	ds_write2_b32 v34, v4, v20 offset0:128 offset1:160
	ds_write2_b32 v34, v5, v21 offset0:192 offset1:224
	v_add_u32_e32 v2, 0x800, v34
	ds_write2_b32 v2, v6, v22 offset1:32
	ds_write2_b32 v2, v7, v23 offset0:64 offset1:96
	ds_write2_b32 v2, v8, v24 offset0:128 offset1:160
	ds_write2_b32 v2, v9, v25 offset0:192 offset1:224
	v_add_u32_e32 v2, 0x1000, v34
	ds_write2_b32 v2, v10, v26 offset1:32
	ds_write2_b32 v2, v11, v27 offset0:64 offset1:96
	ds_write2_b32 v2, v12, v28 offset0:128 offset1:160
	ds_write2_b32 v2, v13, v29 offset0:192 offset1:224
	v_add_u32_e32 v2, 0x1800, v34
	v_add_u32_e32 v18, v75, v50
	ds_write2_b32 v2, v14, v30 offset1:32
	ds_write2_b32 v2, v15, v31 offset0:64 offset1:96
	ds_write2_b32 v2, v16, v32 offset0:128 offset1:160
	ds_write2_b32 v2, v17, v33 offset0:192 offset1:224
	s_waitcnt lgkmcnt(0)
	s_barrier
; #define LAS __attribute__((address_space(3)))
; __device__ __forceinline__ unsigned cvt_pk_bf16(float lo, float hi) { const f32x2 v = {lo, hi}; const bf16x2_t b = __builtin_convertvector(v, bf16x2_t); return __builtin_bit_cast(unsigned, b); }
; template <int KIND>
; __device__ __forceinline__ void mini_task(const Ptrs& P, const bf16* A, int lda, const bf16* B, int ldb, int K, int row0, int cb, LAS unsigned char* lds) {
;     ...
;     const int row = tid >> 4, cg = tid & 15;
;     f32x4 v = {0.f, 0.f, 0.f, 0.f};
; #pragma unroll
;     for (int w = 0; w < 8; ++w) v += *(const LAS f32x4*)((const LAS float*)lds + w * 2048 + row * 64 + cg * 4);
;     const int grow = row0 + row;
;     const bool meta = row0 >= MTOK;
;     if constexpr (KIND == MK_KR) {
;         v *= e_rs;
;         f32x4 o; { o[0] = __shfl_xor(v[0], 1); o[1] = __shfl_xor(v[1], 1); o[2] = __shfl_xor(v[2], 1); o[3] = __shfl_xor(v[3], 1); }
;         const int n = cg & 1, jp = cg >> 1; const f32x4 x1 = n ? o : v, x2 = n ? v : o;
;         if (!meta || row < NMETA) { const int pos = meta ? row : NMETA + (grow & 4095);
;             const f32x4 cs0 = e_cs0, cs1 = e_cs1;
;             const f32x4 cc = {cs0[0], cs0[2], cs1[0], cs1[2]}, sn = {cs0[1], cs0[3], cs1[1], cs1[3]};
;             const f32x4 ov = n ? (x2 * cc + x1 * sn) : (x1 * cc - x2 * sn);
;             u32x2 w; w.x = cvt_pk_bf16(ov[0], ov[1]); w.y = cvt_pk_bf16(ov[2], ov[3]);
;             bf16* d = P.kr_() + ((size_t)(meta ? 0 : (grow >> 12)) * LPAD + pos) * 64 + n * 32 + jp * 4; *(u32x2*)d = w;
;             if (meta) *(u32x2*)(d + (size_t)LPAD * 64) = w; }
;     } else if constexpr (KIND == MK_KVLAT) {
;         v *= e_rs;
;         u32x2 w; w.x = cvt_pk_bf16(v[0], v[1]); w.y = cvt_pk_bf16(v[2], v[3]);
;         *(u32x2*)(P.kvlat_() + (size_t)grow * 512 + cb * 64 + cg * 4) = w;
;         float ss = (v[0] * v[0] + v[1] * v[1]) + (v[2] * v[2] + v[3] * v[3]);
;         ss += __shfl_xor(ss, 1); ss += __shfl_xor(ss, 2); ss += __shfl_xor(ss, 4); ss += __shfl_xor(ss, 8);
;         if (cg == 0) atomicAdd(P.ssq_kv_() + grow, ss);
	ds_read_b128 v[2:5], v18
	ds_read_b128 v[6:9], v18 offset:8192
	ds_read_b128 v[10:13], v18 offset:16384
	s_mov_b32 s17, s13
	v_mov_b32_e32 v71, v43
	s_waitcnt lgkmcnt(2)
	v_pk_add_f32 v[4:5], v[4:5], 0 op_sel_hi:[1,0]
	v_pk_add_f32 v[14:15], v[2:3], 0 op_sel_hi:[1,0]
	s_waitcnt lgkmcnt(1)
	v_pk_add_f32 v[8:9], v[4:5], v[8:9]
	ds_read_b128 v[2:5], v18 offset:24576
	v_pk_add_f32 v[14:15], v[14:15], v[6:7]
	s_waitcnt lgkmcnt(1)
	v_pk_add_f32 v[12:13], v[8:9], v[12:13]
	ds_read_b128 v[6:9], v18 offset:32768
	v_pk_add_f32 v[10:11], v[14:15], v[10:11]
	s_waitcnt lgkmcnt(1)
	v_pk_add_f32 v[12:13], v[12:13], v[4:5]
	v_pk_add_f32 v[14:15], v[10:11], v[2:3]
	ds_read_b128 v[2:5], v18 offset:40960
	s_waitcnt lgkmcnt(1)
	v_pk_add_f32 v[16:17], v[12:13], v[8:9]
	ds_read_b128 v[8:11], v18 offset:49152
	v_pk_add_f32 v[6:7], v[14:15], v[6:7]
	ds_read_b128 v[12:15], v18 offset:57344
	s_waitcnt lgkmcnt(2)
	v_pk_add_f32 v[4:5], v[16:17], v[4:5]
	v_pk_add_f32 v[2:3], v[6:7], v[2:3]
	s_waitcnt lgkmcnt(1)
	v_pk_add_f32 v[4:5], v[4:5], v[10:11]
	v_pk_add_f32 v[2:3], v[2:3], v[8:9]
	s_waitcnt lgkmcnt(0)
	v_pk_add_f32 v[4:5], v[4:5], v[14:15]
	v_pk_add_f32 v[2:3], v[2:3], v[12:13]
	v_pk_mul_f32 v[4:5], v[42:43], v[4:5] op_sel_hi:[0,1]
	v_pk_mul_f32 v[2:3], v[42:43], v[2:3] op_sel_hi:[0,1]
	v_mul_f32_e32 v6, v3, v3
	v_mul_f32_e32 v7, v5, v5
	v_fmac_f32_e32 v6, v2, v2
	v_fmac_f32_e32 v7, v4, v4
	v_and_b32_e32 v8, 64, v77
	v_add_f32_e32 v6, v6, v7
	v_xor_b32_e32 v7, 1, v77
	v_add_u32_e32 v8, 64, v8
	v_cmp_lt_i32_e32 vcc, v7, v8
	s_nop 1
	v_cndmask_b32_e32 v7, v77, v7, vcc
	v_lshlrev_b32_e32 v7, 2, v7
	ds_bpermute_b32 v7, v7, v6
	s_waitcnt lgkmcnt(0)
	v_add_f32_e32 v9, v6, v7
	v_xor_b32_e32 v6, 2, v77
	v_cmp_lt_i32_e32 vcc, v6, v8
	v_cvt_pk_bf16_f32 v7, v4, v5
	s_nop 0
	v_cndmask_b32_e32 v6, v77, v6, vcc
	v_lshlrev_b32_e32 v6, 2, v6
	ds_bpermute_b32 v10, v6, v9
	v_cvt_pk_bf16_f32 v6, v2, v3
	v_xor_b32_e32 v2, 4, v77
	v_cmp_lt_i32_e32 vcc, v2, v8
	s_waitcnt lgkmcnt(0)
	v_add_f32_e32 v9, v9, v10
	v_cndmask_b32_e32 v2, v77, v2, vcc
	v_lshlrev_b32_e32 v2, 2, v2
	ds_bpermute_b32 v10, v2, v9
	v_lshl_add_u64 v[2:3], s[16:17], 1, v[56:57]
	v_lshl_add_u64 v[4:5], v[2:3], 0, v[70:71]
	v_xor_b32_e32 v3, 8, v77
	v_cmp_lt_i32_e32 vcc, v3, v8
	s_waitcnt lgkmcnt(0)
	v_add_f32_e32 v2, v9, v10
	v_cndmask_b32_e32 v3, v77, v3, vcc
	v_lshlrev_b32_e32 v3, 2, v3
	ds_bpermute_b32 v3, v3, v2
	v_add_co_u32_e32 v4, vcc, s28, v4
	s_nop 1
	v_addc_co_u32_e32 v5, vcc, 0, v5, vcc
	global_store_dwordx2 v[4:5], v[6:7], off offset:3968
	s_and_saveexec_b64 s[8:9], s[0:1]
	s_cbranch_execz .LBB0_345
	s_waitcnt lgkmcnt(0)
	v_add_f32_e32 v2, v2, v3
	global_atomic_add_f32 v[58:59], v2, off

; #define SBAR() __builtin_amdgcn_sched_barrier(0)
; template <int KIND>
; __device__ __forceinline__ void mini_task(const Ptrs& P, const bf16* A, int lda, const bf16* B, int ldb, int K, int row0, int cb, LAS unsigned char* lds) {
;     ...
;     if constexpr (KIND == MK_KVUP) e_rs = P.ssq_kv_()[erow]; else e_rs = P.rs1_()[erow];
;     if constexpr (KIND == MK_KR) { const int epos = emeta ? ((tid >> 4) < NMETA ? (tid >> 4) : 0) : NMETA + (erow & 4095); const int ejp = (tid & 15) >> 1;
;         e_cs0 = *(const f32x4*)(P.cs_() + (size_t)epos * 32 + ejp * 4); e_cs1 = *(const f32x4*)(P.cs_() + (size_t)epos * 32 + ejp * 4 + 2); }
;     f32x16 c0 = {}, c1 = {};
;     SBAR();
;     if (kw >= 128) {
;         for (int k = 0; k < kw; k += 128) {
;             bf16x8 a[8], b0[8], b1[8];
; #pragma unroll
;             for (int j = 0; j < 8; ++j) { a[j] = *(const bf16x8*)(ap + k + 16 * j); b0[j] = *(const bf16x8*)(bp + k + 16 * j); b1[j] = *(const bf16x8*)(bp + (size_t)32 * ldb + k + 16 * j); }
;             SBAR();
; #pragma unroll
;             for (int j = 0; j < 8; ++j) { c0 = __builtin_amdgcn_mfma_f32_32x32x16_bf16(a[j], b0[j], c0, 0, 0, 0); c1 = __builtin_amdgcn_mfma_f32_32x32x16_bf16(a[j], b1[j], c1, 0, 0, 0); }
;             SBAR(); }
.LBB0_347:
	v_readfirstlane_b32 s8, v0
	s_lshr_b32 s17, s8, 6
	s_lshl_b64 s[8:9], s[8:9], 3
	s_and_b32 s9, s9, 7
	s_and_b32 s8, s8, 0xfffffe00
	s_lshl_b32 s12, s17, 9
	s_cmpk_lg_i32 s29, 0x100
	v_ashrrev_i32_e32 v67, 31, v66
	v_and_b32_e32 v4, 0xfff, v66
	v_lshl_add_u64 v[2:3], v[66:67], 2, s[14:15]
	v_add_u32_e32 v67, 16, v4
	s_cselect_b64 vcc, -1, 0
	v_cndmask_b32_e32 v4, v51, v67, vcc
	v_lshlrev_b32_e32 v42, 8, v4
	v_lshl_add_u64 v[4:5], v[62:63], 0, v[42:43]
	global_load_dwordx4 v[34:37], v[4:5], off offset:16
	global_load_dword v42, v[2:3], off
	global_load_dwordx4 v[38:41], v[4:5], off
	s_cmpk_eq_i32 s29, 0x100
	s_cselect_b64 s[20:21], -1, 0
	v_lshl_add_u64 v[162:163], v[68:69], 0, s[8:9]
	v_lshl_add_u64 v[164:165], v[60:61], 0, s[12:13]
	v_add_co_u32_e64 v170, s[8:9], s23, v164
	s_nop 1
	v_addc_co_u32_e64 v171, s[8:9], 0, v165, s[8:9]
	global_load_dwordx4 v[18:21], v[162:163], off offset:-256
	global_load_dwordx4 v[78:81], v[162:163], off offset:-224
	global_load_dwordx4 v[2:5], v[164:165], off
	global_load_dwordx4 v[82:85], v[164:165], off offset:32
	global_load_dwordx4 v[22:25], v[170:171], off
	global_load_dwordx4 v[86:89], v[170:171], off offset:32
	global_load_dwordx4 v[90:93], v[162:163], off offset:-192
	global_load_dwordx4 v[94:97], v[162:163], off offset:-160
	global_load_dwordx4 v[98:101], v[164:165], off offset:64
	global_load_dwordx4 v[102:105], v[164:165], off offset:96
	global_load_dwordx4 v[106:109], v[170:171], off offset:64
	global_load_dwordx4 v[110:113], v[170:171], off offset:96
	global_load_dwordx4 v[114:117], v[162:163], off offset:-128
	global_load_dwordx4 v[118:121], v[162:163], off offset:-96
	global_load_dwordx4 v[122:125], v[164:165], off offset:128
	global_load_dwordx4 v[126:129], v[164:165], off offset:160
	global_load_dwordx4 v[130:133], v[170:171], off offset:128
	global_load_dwordx4 v[134:137], v[170:171], off offset:160
	global_load_dwordx4 v[138:141], v[162:163], off offset:-64
	global_load_dwordx4 v[142:145], v[162:163], off offset:-32
	global_load_dwordx4 v[146:149], v[164:165], off offset:192
	global_load_dwordx4 v[150:153], v[164:165], off offset:224
	global_load_dwordx4 v[154:157], v[170:171], off offset:192
	global_load_dwordx4 v[158:161], v[170:171], off offset:224
	global_load_dwordx4 v[180:183], v[162:163], off
	global_load_dwordx4 v[184:187], v[162:163], off offset:32
	global_load_dwordx4 v[188:191], v[164:165], off offset:256
	global_load_dwordx4 v[192:195], v[164:165], off offset:288
	global_load_dwordx4 v[196:199], v[170:171], off offset:256
	global_load_dwordx4 v[200:203], v[170:171], off offset:288
	global_load_dwordx4 v[204:207], v[162:163], off offset:64
	global_load_dwordx4 v[208:211], v[162:163], off offset:96
	global_load_dwordx4 v[212:215], v[164:165], off offset:320
	global_load_dwordx4 v[216:219], v[164:165], off offset:352
	global_load_dwordx4 v[220:223], v[170:171], off offset:320
	global_load_dwordx4 v[224:227], v[170:171], off offset:352
	global_load_dwordx4 v[228:231], v[162:163], off offset:128
	global_load_dwordx4 v[232:235], v[162:163], off offset:160
	global_load_dwordx4 v[236:239], v[164:165], off offset:384
	global_load_dwordx4 v[240:243], v[164:165], off offset:416
	s_waitcnt vmcnt(37)
	v_mfma_f32_32x32x16_bf16 v[2:17], v[18:21], v[2:5], 0
	s_waitcnt vmcnt(35)
	v_mfma_f32_32x32x16_bf16 v[18:33], v[18:21], v[22:25], 0
	v_mfma_f32_32x32x16_bf16 v[2:17], v[78:81], v[82:85], v[2:17]
	s_waitcnt vmcnt(34)
	v_mfma_f32_32x32x16_bf16 v[18:33], v[78:81], v[86:89], v[18:33]
	s_waitcnt vmcnt(31)
	v_mfma_f32_32x32x16_bf16 v[2:17], v[90:93], v[98:101], v[2:17]
	s_waitcnt vmcnt(29)
	v_mfma_f32_32x32x16_bf16 v[18:33], v[90:93], v[106:109], v[18:33]
	v_mfma_f32_32x32x16_bf16 v[2:17], v[94:97], v[102:105], v[2:17]
	s_waitcnt vmcnt(28)
	v_mfma_f32_32x32x16_bf16 v[18:33], v[94:97], v[110:113], v[18:33]
	s_waitcnt vmcnt(25)
	v_mfma_f32_32x32x16_bf16 v[2:17], v[114:117], v[122:125], v[2:17]
	s_waitcnt vmcnt(23)
	v_mfma_f32_32x32x16_bf16 v[18:33], v[114:117], v[130:133], v[18:33]
	v_mfma_f32_32x32x16_bf16 v[2:17], v[118:121], v[126:129], v[2:17]
	s_waitcnt vmcnt(22)
	v_mfma_f32_32x32x16_bf16 v[18:33], v[118:121], v[134:137], v[18:33]
	s_waitcnt vmcnt(19)
	v_mfma_f32_32x32x16_bf16 v[2:17], v[138:141], v[146:149], v[2:17]
	s_waitcnt vmcnt(17)
	v_mfma_f32_32x32x16_bf16 v[18:33], v[138:141], v[154:157], v[18:33]
	v_mfma_f32_32x32x16_bf16 v[2:17], v[142:145], v[150:153], v[2:17]
	s_waitcnt vmcnt(16)
	v_mfma_f32_32x32x16_bf16 v[18:33], v[142:145], v[158:161], v[18:33]
	global_load_dwordx4 v[142:145], v[170:171], off offset:384
	global_load_dwordx4 v[146:149], v[170:171], off offset:416
	global_load_dwordx4 v[150:153], v[162:163], off offset:192
	global_load_dwordx4 v[154:157], v[162:163], off offset:224
	global_load_dwordx4 v[158:161], v[164:165], off offset:448
	s_nop 0
	global_load_dwordx4 v[162:165], v[164:165], off offset:480
	s_nop 0
	global_load_dwordx4 v[166:169], v[170:171], off offset:448
	s_nop 0
	global_load_dwordx4 v[170:173], v[170:171], off offset:480
	s_waitcnt vmcnt(21)
	v_mfma_f32_32x32x16_bf16 v[2:17], v[180:183], v[188:191], v[2:17]
	s_waitcnt vmcnt(19)
	v_mfma_f32_32x32x16_bf16 v[18:33], v[180:183], v[196:199], v[18:33]
	v_mfma_f32_32x32x16_bf16 v[2:17], v[184:187], v[192:195], v[2:17]
	s_waitcnt vmcnt(18)
; template <int KIND>
; __device__ __forceinline__ void mini_task(const Ptrs& P, const bf16* A, int lda, const bf16* B, int ldb, int K, int row0, int cb, LAS unsigned char* lds) {
;     ...
;             for (int j = 0; j < 8; ++j) { a[j] = *(const bf16x8*)(ap + k + 16 * j); b0[j] = *(const bf16x8*)(bp + k + 16 * j); b1[j] = *(const bf16x8*)(bp + (size_t)32 * ldb + k + 16 * j); }
;             SBAR();
; #pragma unroll
;             for (int j = 0; j < 8; ++j) { c0 = __builtin_amdgcn_mfma_f32_32x32x16_bf16(a[j], b0[j], c0, 0, 0, 0); c1 = __builtin_amdgcn_mfma_f32_32x32x16_bf16(a[j], b1[j], c1, 0, 0, 0); }
;             SBAR(); }
;     } else {
;         for (int k = 0; k < kw; k += 64) {
;             bf16x8 a[4], b0[4], b1[4];
; #pragma unroll
;             for (int j = 0; j < 4; ++j) { a[j] = *(const bf16x8*)(ap + k + 16 * j); b0[j] = *(const bf16x8*)(bp + k + 16 * j); b1[j] = *(const bf16x8*)(bp + (size_t)32 * ldb + k + 16 * j); }
;             SBAR();
; #pragma unroll
;             for (int j = 0; j < 4; ++j) { c0 = __builtin_amdgcn_mfma_f32_32x32x16_bf16(a[j], b0[j], c0, 0, 0, 0); c1 = __builtin_amdgcn_mfma_f32_32x32x16_bf16(a[j], b1[j], c1, 0, 0, 0); } } }
;     LAS float* red = (LAS float*)lds + wave * 2048;
; #pragma unroll
;     for (int r = 0; r < 16; ++r) { const int rw = (r & 3) + 8 * (r >> 2) + 4 * hi; red[rw * 64 + r32] = c0[r]; red[rw * 64 + 32 + r32] = c1[r]; }
;     __syncthreads();
;     const int row = tid >> 4, cg = tid & 15;
;     f32x4 v = {0.f, 0.f, 0.f, 0.f};
; #pragma unroll
;     for (int w = 0; w < 8; ++w) v += *(const LAS f32x4*)((const LAS float*)lds + w * 2048 + row * 64 + cg * 4);
;     const int grow = row0 + row;
;     const bool meta = row0 >= MTOK;
;     if constexpr (KIND == MK_KR) {
;         v *= e_rs;
;         f32x4 o; { o[0] = __shfl_xor(v[0], 1); o[1] = __shfl_xor(v[1], 1); o[2] = __shfl_xor(v[2], 1); o[3] = __shfl_xor(v[3], 1); }
;         const int n = cg & 1, jp = cg >> 1; const f32x4 x1 = n ? o : v, x2 = n ? v : o;
;         if (!meta || row < NMETA) { const int pos = meta ? row : NMETA + (grow & 4095);
;             const f32x4 cs0 = e_cs0, cs1 = e_cs1;
;             const f32x4 cc = {cs0[0], cs0[2], cs1[0], cs1[2]}, sn = {cs0[1], cs0[3], cs1[1], cs1[3]};
;             const f32x4 ov = n ? (x2 * cc + x1 * sn) : (x1 * cc - x2 * sn);
;             u32x2 w; w.x = cvt_pk_bf16(ov[0], ov[1]); w.y = cvt_pk_bf16(ov[2], ov[3]);
	v_mfma_f32_32x32x16_bf16 v[18:33], v[184:187], v[200:203], v[18:33]
	s_waitcnt vmcnt(15)
	v_mfma_f32_32x32x16_bf16 v[2:17], v[204:207], v[212:215], v[2:17]
	s_waitcnt vmcnt(13)
	v_mfma_f32_32x32x16_bf16 v[18:33], v[204:207], v[220:223], v[18:33]
	v_mfma_f32_32x32x16_bf16 v[2:17], v[208:211], v[216:219], v[2:17]
	s_waitcnt vmcnt(12)
	v_mfma_f32_32x32x16_bf16 v[18:33], v[208:211], v[224:227], v[18:33]
	s_waitcnt vmcnt(9)
	v_mfma_f32_32x32x16_bf16 v[2:17], v[228:231], v[236:239], v[2:17]
	s_waitcnt vmcnt(7)
	v_mfma_f32_32x32x16_bf16 v[18:33], v[228:231], v[142:145], v[18:33]
	v_mfma_f32_32x32x16_bf16 v[2:17], v[232:235], v[240:243], v[2:17]
	s_waitcnt vmcnt(6)
	v_mfma_f32_32x32x16_bf16 v[18:33], v[232:235], v[146:149], v[18:33]
	s_waitcnt vmcnt(3)
	v_mfma_f32_32x32x16_bf16 v[2:17], v[150:153], v[158:161], v[2:17]
	s_waitcnt vmcnt(1)
	v_mfma_f32_32x32x16_bf16 v[18:33], v[150:153], v[166:169], v[18:33]
	v_mfma_f32_32x32x16_bf16 v[2:17], v[154:157], v[162:165], v[2:17]
	s_waitcnt vmcnt(0)
	v_mfma_f32_32x32x16_bf16 v[18:33], v[154:157], v[170:173], v[18:33]
	v_lshl_add_u32 v71, s17, 13, v74
	s_nop 10
	ds_write2_b32 v71, v2, v18 offset1:32
	ds_write2_b32 v71, v3, v19 offset0:64 offset1:96
	ds_write2_b32 v71, v4, v20 offset0:128 offset1:160
	ds_write2_b32 v71, v5, v21 offset0:192 offset1:224
	v_add_u32_e32 v2, 0x800, v71
	ds_write2_b32 v2, v6, v22 offset1:32
	ds_write2_b32 v2, v7, v23 offset0:64 offset1:96
	ds_write2_b32 v2, v8, v24 offset0:128 offset1:160
	ds_write2_b32 v2, v9, v25 offset0:192 offset1:224
	v_add_u32_e32 v2, 0x1000, v71
	ds_write2_b32 v2, v10, v26 offset1:32
	ds_write2_b32 v2, v11, v27 offset0:64 offset1:96
	ds_write2_b32 v2, v12, v28 offset0:128 offset1:160
	ds_write2_b32 v2, v13, v29 offset0:192 offset1:224
	v_add_u32_e32 v2, 0x1800, v71
	ds_write2_b32 v2, v14, v30 offset1:32
	ds_write2_b32 v2, v15, v31 offset0:64 offset1:96
	ds_write2_b32 v2, v16, v32 offset0:128 offset1:160
	ds_write2_b32 v2, v17, v33 offset0:192 offset1:224
	s_waitcnt lgkmcnt(0)
	s_barrier
	ds_read_b128 v[2:5], v76
	ds_read_b128 v[6:9], v76 offset:8192
	ds_read_b128 v[10:13], v76 offset:16384
	s_or_b64 s[30:31], vcc, s[6:7]
	s_waitcnt lgkmcnt(2)
	v_pk_add_f32 v[4:5], v[4:5], 0 op_sel_hi:[1,0]
	v_pk_add_f32 v[14:15], v[2:3], 0 op_sel_hi:[1,0]
	s_waitcnt lgkmcnt(1)
	v_pk_add_f32 v[8:9], v[4:5], v[8:9]
	ds_read_b128 v[2:5], v76 offset:24576
	v_pk_add_f32 v[14:15], v[14:15], v[6:7]
	s_waitcnt lgkmcnt(1)
	v_pk_add_f32 v[12:13], v[8:9], v[12:13]
	ds_read_b128 v[6:9], v76 offset:32768
	v_pk_add_f32 v[10:11], v[14:15], v[10:11]
	s_waitcnt lgkmcnt(1)
	v_pk_add_f32 v[12:13], v[12:13], v[4:5]
	v_pk_add_f32 v[14:15], v[10:11], v[2:3]
	ds_read_b128 v[2:5], v76 offset:40960
	s_waitcnt lgkmcnt(1)
	v_pk_add_f32 v[16:17], v[12:13], v[8:9]
	ds_read_b128 v[8:11], v76 offset:49152
	v_pk_add_f32 v[6:7], v[14:15], v[6:7]
	ds_read_b128 v[12:15], v76 offset:57344
	s_waitcnt lgkmcnt(2)
	v_pk_add_f32 v[4:5], v[16:17], v[4:5]
	v_pk_add_f32 v[2:3], v[6:7], v[2:3]
	s_waitcnt lgkmcnt(1)
	v_pk_add_f32 v[4:5], v[4:5], v[10:11]
	v_pk_add_f32 v[2:3], v[2:3], v[8:9]
	s_waitcnt lgkmcnt(0)
	v_pk_add_f32 v[6:7], v[4:5], v[14:15]
	v_pk_add_f32 v[2:3], v[2:3], v[12:13]
	s_nop 0
	v_pk_mul_f32 v[4:5], v[42:43], v[2:3] op_sel_hi:[0,1]
	v_pk_mul_f32 v[2:3], v[42:43], v[6:7] op_sel_hi:[0,1]
	v_and_b32_e32 v7, 64, v77
	v_xor_b32_e32 v6, 1, v77
	v_add_u32_e32 v7, 64, v7
	v_cmp_lt_i32_e64 s[8:9], v6, v7
	s_nop 1
	v_cndmask_b32_e64 v6, v77, v6, s[8:9]
	v_lshlrev_b32_e32 v9, 2, v6
	ds_bpermute_b32 v6, v9, v4
	ds_bpermute_b32 v8, v9, v5
	ds_bpermute_b32 v7, v9, v2
	ds_bpermute_b32 v9, v9, v3
	s_and_saveexec_b64 s[8:9], s[30:31]
	s_cbranch_execz .LBB0_335
	s_waitcnt lgkmcnt(0)
	v_cndmask_b32_e64 v11, v3, v9, s[4:5]
	v_cndmask_b32_e64 v10, v2, v7, s[4:5]
	v_cndmask_b32_e64 v12, v4, v6, s[4:5]
	v_cndmask_b32_e64 v4, v6, v4, s[4:5]
	v_cndmask_b32_e64 v3, v9, v3, s[4:5]
	v_cndmask_b32_e64 v2, v7, v2, s[4:5]
	v_mov_b32_e32 v6, v35
	v_mov_b32_e32 v7, v37
	v_cndmask_b32_e64 v13, v5, v8, s[4:5]
	v_cndmask_b32_e64 v5, v8, v5, s[4:5]
	v_pk_mul_f32 v[8:9], v[6:7], v[2:3]
	v_mov_b32_e32 v14, v39
	v_mov_b32_e32 v15, v41
	v_mov_b32_e32 v35, v36
	v_pk_mul_f32 v[16:17], v[14:15], v[4:5]
	v_mov_b32_e32 v39, v40
	v_pk_fma_f32 v[8:9], v[34:35], v[10:11], v[8:9]
	v_pk_mul_f32 v[6:7], v[6:7], v[10:11]
	v_pk_mul_f32 v[10:11], v[14:15], v[12:13]
	v_pk_fma_f32 v[16:17], v[38:39], v[12:13], v[16:17]
	v_pk_fma_f32 v[4:5], v[38:39], v[4:5], v[10:11] neg_lo:[0,0,1] neg_hi:[0,0,1]
	v_pk_fma_f32 v[2:3], v[34:35], v[2:3], v[6:7] neg_lo:[0,0,1] neg_hi:[0,0,1]
	v_cndmask_b32_e64 v4, v16, v4, s[4:5]
	v_cndmask_b32_e64 v6, v8, v2, s[4:5]
	v_cndmask_b32_e64 v2, v17, v5, s[4:5]
	v_cvt_pk_bf16_f32 v2, v4, v2
	v_ashrrev_i32_e32 v4, 12, v66
	v_cndmask_b32_e32 v4, 0, v4, vcc
	v_cndmask_b32_e32 v42, v176, v67, vcc
	v_mul_hi_i32_i24_e32 v5, 0x1040, v4
	v_mul_i32_i24_e32 v4, 0x1040, v4
	v_lshl_add_u64 v[4:5], v[4:5], 0, v[42:43]
	v_cndmask_b32_e64 v3, v9, v3, s[4:5]
	v_lshlrev_b64 v[4:5], 7, v[4:5]
	v_cvt_pk_bf16_f32 v3, v6, v3
	v_lshl_add_u64 v[4:5], v[64:65], 0, v[4:5]
	s_andn2_b64 vcc, exec, s[20:21]
	global_store_dwordx2 v[4:5], v[2:3], off
	s_cbranch_vccnz .LBB0_335
	v_add_co_u32_e32 v4, vcc, 0x82000, v4
	s_nop 1
	v_addc_co_u32_e32 v5, vcc, 0, v5, vcc
	global_store_dwordx2 v[4:5], v[2:3], off
	s_branch .LBB0_335
